# P7 epilogue counted wait: wait only for the eight rstd loads before the row scaling, conv-weight loads waited at their first use
# speedup vs baseline: 1.0008x; 1.0008x over previous
.LBB0_1421:
	v_lshl_add_u32 v122, s60, 8, v1
	v_ashrrev_i32_e32 v123, 31, v122
	s_lshl_b32 s27, s62, 8
	v_lshl_add_u64 v[124:125], v[122:123], 2, s[22:23]
	v_add_u32_e32 v126, 0x80, v122
	v_add_u32_e32 v128, 0x90, v122
	v_add_u32_e32 v130, 0xa0, v122
	v_add_u32_e32 v122, 0xb0, v122
	s_or_b32 s27, s27, s75
	v_ashrrev_i32_e32 v127, 31, v126
	v_ashrrev_i32_e32 v129, 31, v128
	v_ashrrev_i32_e32 v131, 31, v130
	v_ashrrev_i32_e32 v123, 31, v122
	s_ashr_i32 s27, s27, 1
	global_load_dword v194, v[124:125], off
	v_lshl_add_u64 v[126:127], v[126:127], 2, s[22:23]
	v_lshl_add_u64 v[128:129], v[128:129], 2, s[22:23]
	v_lshl_add_u64 v[130:131], v[130:131], 2, s[22:23]
	v_lshl_add_u64 v[122:123], v[122:123], 2, s[22:23]
	global_load_dword v192, v[124:125], off offset:64
	global_load_dword v190, v[124:125], off offset:128
	global_load_dword v188, v[124:125], off offset:192
	global_load_dword v186, v[126:127], off
	global_load_dword v182, v[128:129], off
	global_load_dword v180, v[130:131], off
	global_load_dword v178, v[122:123], off
	v_or_b32_e32 v184, s27, v217
	v_ashrrev_i32_e32 v185, 31, v184
	v_readlane_b32 s36, v245, 19
	v_lshlrev_b64 v[134:135], 2, v[184:185]
	v_readlane_b32 s42, v245, 25
	v_readlane_b32 s43, v245, 26
	v_readlane_b32 s44, v245, 27
	v_readlane_b32 s45, v245, 28
	v_lshl_add_u64 v[196:197], s[42:43], 0, v[134:135]
	v_lshl_add_u64 v[122:123], s[30:31], 0, v[134:135]
	v_lshl_add_u64 v[124:125], s[88:89], 0, v[134:135]
	global_load_dwordx4 v[146:149], v[196:197], off
	global_load_dwordx4 v[142:145], v[122:123], off
	global_load_dwordx4 v[138:141], v[124:125], off
	v_lshl_add_u64 v[198:199], s[44:45], 0, v[134:135]
	v_lshl_add_u64 v[122:123], s[90:91], 0, v[134:135]
	v_lshl_add_u64 v[124:125], s[92:93], 0, v[134:135]
	v_lshl_add_u64 v[126:127], s[94:95], 0, v[134:135]
	v_lshl_add_u64 v[134:135], s[52:53], 0, v[134:135]
	global_load_dwordx4 v[150:153], v[198:199], off
	global_load_dwordx4 v[130:133], v[122:123], off
	s_nop 0
	global_load_dwordx4 v[122:125], v[124:125], off
	s_lshl_b32 s27, s60, 2
	global_load_dwordx4 v[126:129], v[126:127], off
	global_load_dwordx4 v[134:137], v[134:135], off
	s_add_i32 s60, s27, s33
	v_lshl_or_b32 v179, s60, 6, v166
	v_readlane_b32 s37, v245, 20
	v_readlane_b32 s38, v245, 21
	v_readlane_b32 s39, v245, 22
	v_readlane_b32 s40, v245, 23
	v_readlane_b32 s41, v245, 24
	v_readlane_b32 s46, v245, 29
	v_readlane_b32 s47, v245, 30
	v_readlane_b32 s48, v245, 31
	v_readlane_b32 s49, v245, 32
	v_readlane_b32 s50, v245, 33
	v_readlane_b32 s51, v245, 34
	s_waitcnt vmcnt(8)
	v_pk_mul_f32 v[160:161], v[160:161], v[194:195] op_sel_hi:[1,0]
	v_pk_mul_f32 v[158:159], v[158:159], v[194:195] op_sel_hi:[1,0]
	v_pk_mul_f32 v[156:157], v[156:157], v[194:195] op_sel_hi:[1,0]
	v_pk_mul_f32 v[154:155], v[154:155], v[194:195] op_sel_hi:[1,0]
	v_mov_b32_dpp v204, v158 row_ror:1 row_mask:0xf bank_mask:0xf
	v_mov_b32_dpp v205, v159 row_ror:1 row_mask:0xf bank_mask:0xf
	v_mov_b32_dpp v206, v160 row_ror:1 row_mask:0xf bank_mask:0xf
	v_mov_b32_dpp v207, v161 row_ror:1 row_mask:0xf bank_mask:0xf
	v_mov_b32_dpp v208, v158 row_ror:2 row_mask:0xf bank_mask:0xf
	v_mov_b32_dpp v209, v159 row_ror:2 row_mask:0xf bank_mask:0xf
	v_mov_b32_dpp v210, v160 row_ror:2 row_mask:0xf bank_mask:0xf
	v_mov_b32_dpp v211, v161 row_ror:2 row_mask:0xf bank_mask:0xf
	v_mov_b32_dpp v200, v154 row_ror:1 row_mask:0xf bank_mask:0xf
	v_mov_b32_dpp v201, v155 row_ror:1 row_mask:0xf bank_mask:0xf
	v_mov_b32_dpp v202, v156 row_ror:1 row_mask:0xf bank_mask:0xf
	v_mov_b32_dpp v203, v157 row_ror:1 row_mask:0xf bank_mask:0xf
	v_mov_b32_dpp v212, v154 row_ror:2 row_mask:0xf bank_mask:0xf
	v_mov_b32_dpp v213, v155 row_ror:2 row_mask:0xf bank_mask:0xf
	v_mov_b32_dpp v214, v156 row_ror:2 row_mask:0xf bank_mask:0xf
	v_mov_b32_dpp v215, v157 row_ror:2 row_mask:0xf bank_mask:0xf
	v_mov_b32_dpp v204, v158 row_shr:1 row_mask:0xf bank_mask:0xf
	v_mov_b32_dpp v205, v159 row_shr:1 row_mask:0xf bank_mask:0xf
	v_mov_b32_dpp v206, v160 row_shr:1 row_mask:0xf bank_mask:0xf
	v_mov_b32_dpp v207, v161 row_shr:1 row_mask:0xf bank_mask:0xf
	v_mov_b32_dpp v208, v158 row_shr:2 row_mask:0xf bank_mask:0xf
	v_mov_b32_dpp v209, v159 row_shr:2 row_mask:0xf bank_mask:0xf
	v_mov_b32_dpp v210, v160 row_shr:2 row_mask:0xf bank_mask:0xf
	v_mov_b32_dpp v211, v161 row_shr:2 row_mask:0xf bank_mask:0xf
	v_mov_b32_dpp v200, v154 row_shr:1 row_mask:0xf bank_mask:0xf
	v_mov_b32_dpp v201, v155 row_shr:1 row_mask:0xf bank_mask:0xf
	v_mov_b32_dpp v202, v156 row_shr:1 row_mask:0xf bank_mask:0xf
	v_mov_b32_dpp v203, v157 row_shr:1 row_mask:0xf bank_mask:0xf
	v_mov_b32_dpp v212, v154 row_shr:2 row_mask:0xf bank_mask:0xf
	v_mov_b32_dpp v213, v155 row_shr:2 row_mask:0xf bank_mask:0xf
	v_mov_b32_dpp v214, v156 row_shr:2 row_mask:0xf bank_mask:0xf
	v_mov_b32_dpp v215, v157 row_shr:2 row_mask:0xf bank_mask:0xf
	s_and_saveexec_b64 s[62:63], s[6:7]
	s_cbranch_execz .LBB0_1423
	s_waitcnt vmcnt(0)
	v_pk_fma_f32 v[210:211], v[148:149], v[210:211], v[152:153]
	v_pk_fma_f32 v[208:209], v[146:147], v[208:209], v[150:151]
	v_pk_fma_f32 v[206:207], v[144:145], v[206:207], v[210:211]
	v_pk_fma_f32 v[204:205], v[142:143], v[204:205], v[208:209]
	v_pk_fma_f32 v[206:207], v[160:161], v[140:141], v[206:207]
	v_pk_fma_f32 v[204:205], v[158:159], v[138:139], v[204:205]
	v_mul_f32_e32 v181, 0xbfb8aa3b, v207
	v_exp_f32_e32 v181, v181
	v_mul_f32_e32 v183, 0xbfb8aa3b, v206
	v_exp_f32_e32 v183, v183
	v_mul_f32_e32 v187, 0xbfb8aa3b, v204
	v_add_f32_e32 v181, 1.0, v181
	v_rcp_f32_e32 v209, v181
	v_add_f32_e32 v181, 1.0, v183
	v_mul_f32_e32 v183, 0xbfb8aa3b, v205
	v_exp_f32_e32 v183, v183
	v_exp_f32_e32 v187, v187
	v_rcp_f32_e32 v208, v181
	v_pk_fma_f32 v[212:213], v[130:131], v[212:213], v[134:135]
	v_add_f32_e32 v181, 1.0, v183
	v_rcp_f32_e32 v211, v181
	v_add_f32_e32 v181, 1.0, v187
	v_rcp_f32_e32 v210, v181
	v_pk_fma_f32 v[214:215], v[132:133], v[214:215], v[136:137]
	v_pk_fma_f32 v[200:201], v[122:123], v[200:201], v[212:213]
	v_pk_fma_f32 v[202:203], v[124:125], v[202:203], v[214:215]
	v_pk_fma_f32 v[200:201], v[154:155], v[126:127], v[200:201]
	v_pk_mul_f32 v[204:205], v[204:205], v[210:211]
	v_pk_fma_f32 v[202:203], v[156:157], v[128:129], v[202:203]
	v_pk_mul_f32 v[200:201], v[204:205], v[200:201]
	v_pk_mul_f32 v[204:205], v[206:207], v[208:209]
	v_cvt_pk_bf16_f32 v200, v200, v201
	v_pk_mul_f32 v[202:203], v[204:205], v[202:203]
	v_mov_b64_e32 v[204:205], s[18:19]
	v_mad_i64_i32 v[204:205], s[42:43], v179, s82, v[204:205]
	v_lshl_add_u64 v[204:205], v[184:185], 1, v[204:205]
	v_cvt_pk_bf16_f32 v201, v202, v203
	global_store_dwordx2 v[204:205], v[200:201], off
